# pass2: raw rows requested two chunks ahead (second register buffer, parity-selected top block); on top of v8
# baseline (speedup 1.0000x reference)
.LBB0_1328:
	s_or_b64 exec, exec, s[22:23]
	s_lshl_b32 s19, s24, 1
	s_and_b32 s22, s25, 0xf00
	s_and_b32 s23, s19, 0x300
	s_lshl_b32 s19, s26, 2
	s_add_u32 s20, s22, s20
	v_or_b32_e32 v60, s27, v107
	s_addc_u32 s21, 0, s21
	v_mov_b32_e32 v58, s23
	v_mov_b32_e32 v59, v16
	v_lshlrev_b32_e32 v123, 1, v60
	v_lshl_add_u64 v[60:61], s[20:21], 0, v[74:75]
	s_movk_i32 s22, 0x1600
	s_waitcnt lgkmcnt(0)
	s_barrier
	v_lshlrev_b64 v[62:63], 11, v[60:61]
	v_mad_u64_u32 v[58:59], s[20:21], v60, s22, v[58:59]
	v_or_b32_e32 v62, s23, v62
	v_mad_i32_i24 v59, v61, s22, v59
	s_waitcnt vmcnt(12)
	v_lshlrev_b32_e32 v26, 16, v38
	v_and_b32_e32 v27, 0xffff0000, v38
	v_lshlrev_b32_e32 v28, 16, v39
	v_and_b32_e32 v29, 0xffff0000, v39
	s_waitcnt vmcnt(11)
	v_lshlrev_b32_e32 v30, 16, v34
	v_and_b32_e32 v31, 0xffff0000, v34
	v_lshlrev_b32_e32 v32, 16, v35
	v_and_b32_e32 v33, 0xffff0000, v35
	s_waitcnt vmcnt(10)
	v_lshlrev_b32_e32 v34, 16, v36
	v_and_b32_e32 v35, 0xffff0000, v36
	v_lshlrev_b32_e32 v36, 16, v37
	v_and_b32_e32 v37, 0xffff0000, v37
	s_waitcnt vmcnt(9)
	v_lshlrev_b32_e32 v38, 16, v40
	v_and_b32_e32 v39, 0xffff0000, v40
	v_lshlrev_b32_e32 v40, 16, v41
	v_and_b32_e32 v41, 0xffff0000, v41
	s_waitcnt vmcnt(8)
	v_lshlrev_b32_e32 v42, 16, v44
	v_and_b32_e32 v43, 0xffff0000, v44
	v_lshlrev_b32_e32 v44, 16, v45
	v_and_b32_e32 v45, 0xffff0000, v45
	s_waitcnt vmcnt(7)
	v_lshlrev_b32_e32 v46, 16, v48
	v_and_b32_e32 v47, 0xffff0000, v48
	v_lshlrev_b32_e32 v48, 16, v49
	v_and_b32_e32 v49, 0xffff0000, v49
	s_waitcnt vmcnt(6)
	v_lshlrev_b32_e32 v50, 16, v52
	v_and_b32_e32 v51, 0xffff0000, v52
	v_lshlrev_b32_e32 v52, 16, v53
	v_and_b32_e32 v53, 0xffff0000, v53
	s_waitcnt vmcnt(5)
	v_lshlrev_b32_e32 v54, 16, v56
	v_and_b32_e32 v55, 0xffff0000, v56
	v_lshlrev_b32_e32 v56, 16, v57
	v_and_b32_e32 v57, 0xffff0000, v57
	v_add_lshl_u32 v124, s27, v77, 2
	v_lshl_or_b32 v222, s27, 1, v104
	v_mul_u32_u24_e32 v236, 0x140, v95
	v_lshlrev_b32_e32 v224, 1, v222
	v_add_u32_e32 v236, v236, v222
	global_load_dwordx4 v[224:227], v224, s[70:71]
	v_lshl_add_u64 v[88:89], v[82:83], 0, v[62:63]
	v_lshl_add_u64 v[90:91], v[84:85], 0, v[58:59]
	global_load_dwordx4 v[180:183], v[90:91], off offset:-2048
	global_load_dwordx4 v[184:187], v[90:91], off offset:-1024
	global_load_dwordx4 v[188:191], v[90:91], off
	global_load_dwordx4 v[192:195], v[90:91], off offset:1024
	s_mov_b32 s26, 0
	s_branch .LBB0_1331

.LBB0_1330:
	s_add_i32 s26, s26, 1
	s_mov_b64 s[20:21], 0x10000
	v_lshl_add_u32 v160, v95, 5, s27
	ds_read_b128 v[148:151], v160 offset:57344
	ds_read_b128 v[152:155], v160 offset:57360
	ds_read_b128 v[156:159], v160 offset:57856
	ds_read_b128 v[162:165], v160 offset:57872
	v_add3_u32 v125, s27, v109, v222
	ds_read_b64 v[166:167], v125 offset:48128
	ds_read_b64 v[168:169], v125 offset:52480
	s_waitcnt vmcnt(8)
	s_waitcnt lgkmcnt(4)
	v_add_f32_e32 v170, v148, v149
	v_add_f32_e32 v171, v150, v151
	v_add_f32_e32 v172, v152, v153
	v_add_f32_e32 v170, v170, v171
	v_add_f32_e32 v173, v154, v155
	v_add_f32_e32 v172, v172, v173
	v_add_f32_e32 v170, v170, v172
	v_fmamk_f32 v170, v170, 0x3c000000, v218
	v_rsq_f32_e32 v170, v170
	s_waitcnt lgkmcnt(2)
	v_add_f32_e32 v174, v156, v157
	v_add_f32_e32 v175, v158, v159
	v_add_f32_e32 v176, v162, v163
	v_add_f32_e32 v174, v174, v175
	v_add_f32_e32 v177, v164, v165
	v_add_f32_e32 v176, v176, v177
	v_add_f32_e32 v174, v174, v176
	v_fmamk_f32 v174, v174, 0x3c000000, v218
	v_rsq_f32_e32 v174, v174
	s_waitcnt lgkmcnt(0)
	v_lshlrev_b32_e32 v178, 16, v166
	v_and_b32_e32 v179, 0xffff0000, v166
	v_lshlrev_b32_e32 v200, 16, v167
	v_and_b32_e32 v201, 0xffff0000, v167
	v_lshlrev_b32_e32 v202, 16, v168
	v_and_b32_e32 v203, 0xffff0000, v168
	v_lshlrev_b32_e32 v204, 16, v169
	v_and_b32_e32 v205, 0xffff0000, v169
	v_mul_f32_e32 v206, v62, v170
	v_mul_f32_e32 v207, v63, v170
	v_mul_f32_e32 v208, v64, v170
	v_mul_f32_e32 v209, v65, v170
	v_mul_f32_e32 v210, v58, v174
	v_mul_f32_e32 v211, v59, v174
	v_mul_f32_e32 v212, v60, v174
	v_mul_f32_e32 v213, v61, v174
	v_mul_f32_e32 v206, v224, v206
	v_mul_f32_e32 v207, v225, v207
	v_mul_f32_e32 v208, v226, v208
	v_mul_f32_e32 v209, v227, v209
	v_mul_f32_e32 v210, v224, v210
	v_mul_f32_e32 v211, v225, v211
	v_mul_f32_e32 v212, v226, v212
	v_mul_f32_e32 v213, v227, v213
	v_mul_f32_e32 v206, v206, v178
	v_mul_f32_e32 v207, v207, v179
	v_mul_f32_e32 v208, v208, v200
	v_mul_f32_e32 v209, v209, v201
	v_mul_f32_e32 v210, v210, v202
	v_mul_f32_e32 v211, v211, v203
	v_mul_f32_e32 v212, v212, v204
	v_mul_f32_e32 v213, v213, v205
	v_cvt_pk_bf16_f32 v148, v206, v207
	v_cvt_pk_bf16_f32 v149, v208, v209
	v_cvt_pk_bf16_f32 v150, v210, v211
	v_cvt_pk_bf16_f32 v151, v212, v213
	ds_write_b64 v125, v[148:149] offset:8704
	ds_write_b64 v125, v[150:151] offset:13056
	s_cmp_lg_u32 s26, 8
	s_waitcnt lgkmcnt(0)
	s_barrier
	v_add3_u32 v58, s27, v93, v80
	ds_read_b128 v[58:61], v58 offset:8704
	s_waitcnt lgkmcnt(0)
	global_store_dwordx4 v[88:89], v[58:61], off
	v_lshl_add_u64 v[88:89], v[88:89], 0, s[20:21]
	s_mov_b64 s[20:21], 0x2c000
	v_lshl_add_u64 v[90:91], v[90:91], 0, s[20:21]
	s_cbranch_scc0 .LBB0_1325
.LBB0_1331:
	s_and_b32 s22, s26, 1
	s_xor_b32 s20, s22, 1
	s_mul_i32 s20, s20, 0xe400
	s_add_i32 s28, s20, 0
	s_cmp_lg_u32 s26, 7
	s_cselect_b64 s[20:21], -1, 0
	s_cmp_eq_u32 s26, 7
	s_cbranch_scc1 .LBB0_1334
	v_add3_u32 v58, s28, v93, v80
	v_add3_u32 v59, s28, v94, v80
	s_bitcmp1_b32 s26, 0
	s_cbranch_scc1 .Lp2_rawB
	s_cmp_eq_u32 s26, 6
	s_cbranch_scc1 .Lp2_rawA6
	s_waitcnt vmcnt(8)
	ds_write_b128 v58, v[8:11]
	s_waitcnt vmcnt(7)
	ds_write_b128 v59, v[12:15] offset:17408
	s_waitcnt vmcnt(6)
	ds_write_b128 v59, v[18:21] offset:37888
	s_waitcnt vmcnt(5)
	ds_write_b128 v58, v[22:25] offset:48128
	s_cmp_gt_u32 s26, 4
	s_cbranch_scc1 .LBB0_1334
	s_mov_b64 vcc, 0x2c000
	v_lshl_add_u64 v[196:197], v[90:91], 0, vcc
	global_load_dwordx4 v[8:11], v[196:197], off offset:-2048
	global_load_dwordx4 v[12:15], v[196:197], off offset:-1024
	global_load_dwordx4 v[18:21], v[196:197], off
	global_load_dwordx4 v[22:25], v[196:197], off offset:1024
	s_branch .LBB0_1334
.Lp2_rawA6:
	s_waitcnt vmcnt(2)
	ds_write_b128 v58, v[8:11]
	ds_write_b128 v59, v[12:15] offset:17408
	ds_write_b128 v59, v[18:21] offset:37888
	ds_write_b128 v58, v[22:25] offset:48128
	s_branch .LBB0_1334
.Lp2_rawB:
	s_waitcnt vmcnt(8)
	ds_write_b128 v58, v[180:183]
	s_waitcnt vmcnt(7)
	ds_write_b128 v59, v[184:187] offset:17408
	s_waitcnt vmcnt(6)
	ds_write_b128 v59, v[188:191] offset:37888
	s_waitcnt vmcnt(5)
	ds_write_b128 v58, v[192:195] offset:48128
	s_cmp_gt_u32 s26, 4
	s_cbranch_scc1 .LBB0_1334
	s_mov_b64 vcc, 0x2c000
	v_lshl_add_u64 v[196:197], v[90:91], 0, vcc
	global_load_dwordx4 v[180:183], v[196:197], off offset:-2048
	global_load_dwordx4 v[184:187], v[196:197], off offset:-1024
	global_load_dwordx4 v[188:191], v[196:197], off
	global_load_dwordx4 v[192:195], v[196:197], off offset:1024
.LBB0_1334:
	s_mul_i32 s22, s22, 0xe400
	s_add_i32 s27, s22, 0
	v_add3_u32 v147, s27, v104, v109
	s_add_i32 s29, s27, s19
	ds_read_b64 v[148:149], v147
	ds_read_b64 v[150:151], v147 offset:32
	ds_read_b64 v[152:153], v147 offset:4352
	ds_read_b64 v[154:155], v147 offset:4384
	ds_read_b64 v[196:197], v147 offset:8704
	ds_read_b64 v[198:199], v147 offset:8736
	ds_read_b64 v[200:201], v147 offset:13056
	ds_read_b64 v[202:203], v147 offset:13088
	v_cvt_pk_bf16_f32 v126, v26, v27
	v_cvt_pk_bf16_f32 v127, v28, v29
	v_cvt_pk_bf16_f32 v128, v30, v31
	v_cvt_pk_bf16_f32 v129, v32, v33
	ds_read_b64 v[156:157], v147 offset:64
	ds_read_b64 v[158:159], v147 offset:96
	ds_read_b64 v[160:161], v147 offset:4416
	ds_read_b64 v[162:163], v147 offset:4448
	ds_read_b64 v[204:205], v147 offset:8768
	ds_read_b64 v[206:207], v147 offset:8800
	s_waitcnt lgkmcnt(12)
	v_mfma_f32_16x16x32_bf16 v[62:65], v[126:129], v[148:151], 0
	ds_read_b64 v[208:209], v147 offset:13120
	ds_read_b64 v[210:211], v147 offset:13152
	v_cvt_pk_bf16_f32 v130, v34, v35
	v_cvt_pk_bf16_f32 v131, v36, v37
	v_cvt_pk_bf16_f32 v132, v38, v39
	v_cvt_pk_bf16_f32 v133, v40, v41
	s_waitcnt lgkmcnt(12)
	v_mfma_f32_16x16x32_bf16 v[58:61], v[126:129], v[152:155], 0
	s_waitcnt lgkmcnt(10)
	v_mfma_f32_16x16x32_bf16 v[164:167], v[196:199], v[148:151], 0
	v_mfma_f32_16x16x32_bf16 v[168:171], v[196:199], v[152:155], 0
	s_waitcnt lgkmcnt(8)
	v_mfma_f32_16x16x32_bf16 v[172:175], v[200:203], v[152:155], 0
	ds_read_b64 v[148:149], v147 offset:128
	ds_read_b64 v[150:151], v147 offset:160
	ds_read_b64 v[152:153], v147 offset:4480
	ds_read_b64 v[154:155], v147 offset:4512
	ds_read_b64 v[196:197], v147 offset:8832
	ds_read_b64 v[198:199], v147 offset:8864
	s_waitcnt lgkmcnt(12)
	v_mfma_f32_16x16x32_bf16 v[62:65], v[130:133], v[156:159], v[62:65]
	ds_read_b64 v[200:201], v147 offset:13184
	ds_read_b64 v[202:203], v147 offset:13216
	v_cvt_pk_bf16_f32 v134, v42, v43
	v_cvt_pk_bf16_f32 v135, v44, v45
	v_cvt_pk_bf16_f32 v136, v46, v47
	v_cvt_pk_bf16_f32 v137, v48, v49
	s_waitcnt lgkmcnt(12)
	v_mfma_f32_16x16x32_bf16 v[58:61], v[130:133], v[160:163], v[58:61]
	s_waitcnt lgkmcnt(10)
	v_mfma_f32_16x16x32_bf16 v[164:167], v[204:207], v[156:159], v[164:167]
	v_mfma_f32_16x16x32_bf16 v[168:171], v[204:207], v[160:163], v[168:171]
	s_waitcnt lgkmcnt(8)
	v_mfma_f32_16x16x32_bf16 v[172:175], v[208:211], v[160:163], v[172:175]
	ds_read_b64 v[156:157], v147 offset:192
	ds_read_b64 v[158:159], v147 offset:224
	ds_read_b64 v[160:161], v147 offset:4544
	ds_read_b64 v[162:163], v147 offset:4576
	ds_read_b64 v[204:205], v147 offset:8896
	ds_read_b64 v[206:207], v147 offset:8928
	s_waitcnt lgkmcnt(12)
	v_mfma_f32_16x16x32_bf16 v[62:65], v[134:137], v[148:151], v[62:65]
	ds_read_b64 v[208:209], v147 offset:13248
	ds_read_b64 v[210:211], v147 offset:13280
	v_cvt_pk_bf16_f32 v138, v50, v51
	v_cvt_pk_bf16_f32 v139, v52, v53
	v_cvt_pk_bf16_f32 v140, v54, v55
	v_cvt_pk_bf16_f32 v141, v56, v57
	s_waitcnt lgkmcnt(12)
	v_mfma_f32_16x16x32_bf16 v[58:61], v[134:137], v[152:155], v[58:61]
	s_waitcnt lgkmcnt(10)
	v_mfma_f32_16x16x32_bf16 v[164:167], v[196:199], v[148:151], v[164:167]
	v_mfma_f32_16x16x32_bf16 v[168:171], v[196:199], v[152:155], v[168:171]
	s_waitcnt lgkmcnt(8)
	v_mfma_f32_16x16x32_bf16 v[172:175], v[200:203], v[152:155], v[172:175]
	v_add_u32_e32 v176, s27, v106
	v_add_u32_e32 v68, v176, v123
	ds_read_b64_tr_b16 v[66:67], v68 offset:37888
	ds_read_b64_tr_b16 v[68:69], v68 offset:43008
	s_waitcnt lgkmcnt(8)
	v_mfma_f32_16x16x32_bf16 v[62:65], v[138:141], v[156:159], v[62:65]
	s_waitcnt lgkmcnt(6)
	v_mfma_f32_16x16x32_bf16 v[58:61], v[138:141], v[160:163], v[58:61]
	s_waitcnt lgkmcnt(4)
	v_mfma_f32_16x16x32_bf16 v[164:167], v[204:207], v[156:159], v[164:167]
	v_mfma_f32_16x16x32_bf16 v[168:171], v[204:207], v[160:163], v[168:171]
	s_waitcnt lgkmcnt(2)
	v_mfma_f32_16x16x32_bf16 v[172:175], v[208:211], v[160:163], v[172:175]
	v_add_u32_e32 v125, s27, v105
	v_add_u32_e32 v134, v176, v110
	v_mov_b32_e32 v177, s55
	v_mov_b32_e32 v72, v16
	v_mov_b32_e32 v73, v16
	s_nop 0
	v_cndmask_b32_e64 v165, 0, v165, s[6:7]
	v_cndmask_b32_e64 v166, v166, 0, s[8:9]
	v_cndmask_b32_e64 v167, v167, 0, s[10:11]
	v_cndmask_b32_e64 v164, v164, v177, s[4:5]
	v_cvt_pk_bf16_f32 v70, v164, v165
	v_cvt_pk_bf16_f32 v71, v166, v167
	v_cndmask_b32_e64 v172, v172, v177, s[4:5]
	v_cndmask_b32_e64 v173, v173, 0, s[12:13]
	v_cndmask_b32_e64 v174, v174, 0, s[14:15]
	v_cndmask_b32_e64 v175, v175, 0, s[16:17]
	s_waitcnt lgkmcnt(0)
	v_mfma_f32_16x16x32_bf16 v[62:65], v[66:69], v[70:73], v[62:65]
	v_cvt_pk_bf16_f32 v70, v168, v169
	v_cvt_pk_bf16_f32 v71, v170, v171
	v_cvt_pk_bf16_f32 v72, v172, v173
	v_cvt_pk_bf16_f32 v73, v174, v175
	s_nop 1
	v_mfma_f32_16x16x32_bf16 v[58:61], v[66:69], v[70:73], v[58:61]
	ds_read_b128 v[70:73], v125 offset:56832
	ds_read_b64_tr_b16 v[128:129], v134 offset:32768
	ds_read_b64_tr_b16 v[126:127], v134 offset:27648
	ds_read_b64_tr_b16 v[130:131], v134 offset:27680
	s_waitcnt lgkmcnt(3)
	v_pk_mul_f32 v[26:27], v[26:27], v[70:71]
	v_add_u32_e32 v70, s27, v111
	v_pk_mul_f32 v[28:29], v[28:29], v[72:73]
	ds_read_b128 v[70:73], v70 offset:56832
	ds_read_b64_tr_b16 v[132:133], v134 offset:32800
	s_waitcnt lgkmcnt(3)
	v_mfma_f32_16x16x32_bf16 v[26:29], v[126:129], v[66:69], v[26:29]
	s_waitcnt lgkmcnt(1)
	v_pk_mul_f32 v[32:33], v[32:33], v[72:73]
	v_pk_mul_f32 v[30:31], v[30:31], v[70:71]
	ds_read_b128 v[70:73], v125 offset:56960
	ds_read_b64_tr_b16 v[126:127], v134 offset:27712
	ds_read_b64_tr_b16 v[128:129], v134 offset:32832
	s_waitcnt lgkmcnt(3)
	v_mfma_f32_16x16x32_bf16 v[30:33], v[130:133], v[66:69], v[30:33]
	s_waitcnt lgkmcnt(2)
	v_pk_mul_f32 v[36:37], v[36:37], v[72:73]
	v_pk_mul_f32 v[34:35], v[34:35], v[70:71]
	s_waitcnt lgkmcnt(0)
	s_nop 0
	v_mfma_f32_16x16x32_bf16 v[34:37], v[126:129], v[66:69], v[34:37]
	ds_read_b128 v[70:73], v125 offset:57024
	ds_read_b64_tr_b16 v[126:127], v134 offset:27744
	ds_read_b64_tr_b16 v[128:129], v134 offset:32864
	s_waitcnt lgkmcnt(2)
	v_pk_mul_f32 v[40:41], v[40:41], v[72:73]
	v_pk_mul_f32 v[38:39], v[38:39], v[70:71]
	s_waitcnt lgkmcnt(0)
	s_nop 0
	v_mfma_f32_16x16x32_bf16 v[38:41], v[126:129], v[66:69], v[38:41]
	ds_read_b128 v[70:73], v125 offset:57088
	ds_read_b64_tr_b16 v[126:127], v134 offset:27776
	ds_read_b64_tr_b16 v[128:129], v134 offset:32896
	s_waitcnt lgkmcnt(2)
	v_pk_mul_f32 v[44:45], v[44:45], v[72:73]
	v_pk_mul_f32 v[42:43], v[42:43], v[70:71]
	s_waitcnt lgkmcnt(0)
	s_nop 0
	v_mfma_f32_16x16x32_bf16 v[42:45], v[126:129], v[66:69], v[42:45]
	ds_read_b128 v[70:73], v125 offset:57152
	ds_read_b64_tr_b16 v[126:127], v134 offset:27808
	ds_read_b64_tr_b16 v[128:129], v134 offset:32928
	s_waitcnt lgkmcnt(2)
	v_pk_mul_f32 v[48:49], v[48:49], v[72:73]
	v_pk_mul_f32 v[46:47], v[46:47], v[70:71]
	s_waitcnt lgkmcnt(0)
	s_nop 0
	v_mfma_f32_16x16x32_bf16 v[46:49], v[126:129], v[66:69], v[46:49]
	ds_read_b128 v[70:73], v125 offset:57216
	ds_read_b64_tr_b16 v[126:127], v134 offset:27840
	ds_read_b64_tr_b16 v[128:129], v134 offset:32960
	s_waitcnt lgkmcnt(2)
	v_pk_mul_f32 v[52:53], v[52:53], v[72:73]
	v_pk_mul_f32 v[50:51], v[50:51], v[70:71]
	s_waitcnt lgkmcnt(0)
	s_nop 0
	v_mfma_f32_16x16x32_bf16 v[50:53], v[126:129], v[66:69], v[50:53]
	ds_read_b128 v[70:73], v125 offset:57280
	ds_read_b64_tr_b16 v[126:127], v134 offset:27872
	ds_read_b64_tr_b16 v[128:129], v134 offset:32992
	s_waitcnt lgkmcnt(2)
	v_pk_mul_f32 v[56:57], v[56:57], v[72:73]
	v_pk_mul_f32 v[54:55], v[54:55], v[70:71]
	s_waitcnt lgkmcnt(0)
	s_nop 0
	v_mfma_f32_16x16x32_bf16 v[54:57], v[126:129], v[66:69], v[54:57]
	v_mul_f32_e32 v148, v62, v62
	v_mul_f32_e32 v149, v58, v58
	v_fmac_f32_e32 v148, v63, v63
	v_fmac_f32_e32 v149, v59, v59
	v_fmac_f32_e32 v148, v64, v64
	v_fmac_f32_e32 v149, v60, v60
	v_fmac_f32_e32 v148, v65, v65
	v_fmac_f32_e32 v149, v61, v61
	v_lshl_add_u32 v156, v77, 5, s29
	s_nop 0
	v_permlane16_swap_b32_e32 v148, v149
	v_add_f32_e32 v148, v148, v149
	v_mov_b32_e32 v149, v148
	s_nop 1
	v_permlane32_swap_b32_e32 v148, v149
	v_add_f32_e32 v148, v148, v149
	s_mov_b64 s[22:23], exec
	s_mov_b32 exec_hi, 0
	ds_write_b32 v156, v148 offset:57344
	s_mov_b64 exec, s[22:23]
	s_waitcnt lgkmcnt(0)
	s_barrier
	s_andn2_b64 vcc, exec, s[20:21]
	s_cbranch_vccnz .LBB0_1330
	v_add3_u32 v68, s28, v96, v120
	ds_read_b64_tr_b16 v[66:67], v68 offset:17408
	ds_read_b64_tr_b16 v[68:69], v68 offset:18688
	v_add_u32_e32 v138, s28, v236
	v_add3_u32 v139, s28, v109, v222
	ds_read_b64 v[148:149], v138 offset:17408
	ds_read_b64 v[150:151], v138 offset:22528
	ds_read_b64 v[152:153], v139
	ds_read_b64 v[154:155], v139 offset:4352
	s_waitcnt lgkmcnt(4)
	v_mfma_f32_16x16x32_bf16 v[70:73], v[66:69], v[4:7], 0
	v_mfma_f32_16x16x32_bf16 v[66:69], v[66:69], v[0:3], 0
	s_mov_b32 s23, 0x42e60000
	s_waitcnt lgkmcnt(0)
	v_lshlrev_b32_e32 v156, 16, v148
	v_and_b32_e32 v157, 0xffff0000, v148
	v_lshlrev_b32_e32 v158, 16, v149
	v_and_b32_e32 v159, 0xffff0000, v149
	v_lshlrev_b32_e32 v160, 16, v150
	v_and_b32_e32 v161, 0xffff0000, v150
	v_lshlrev_b32_e32 v162, 16, v151
	v_and_b32_e32 v163, 0xffff0000, v151
	v_lshlrev_b32_e32 v196, 16, v152
	v_and_b32_e32 v197, 0xffff0000, v152
	v_lshlrev_b32_e32 v198, 16, v153
	v_and_b32_e32 v199, 0xffff0000, v153
	v_lshlrev_b32_e32 v200, 16, v154
	v_and_b32_e32 v201, 0xffff0000, v154
	v_lshlrev_b32_e32 v202, 16, v155
	v_and_b32_e32 v203, 0xffff0000, v155
	v_exp_f32_e32 v156, v156
	v_exp_f32_e32 v157, v157
	v_exp_f32_e32 v158, v158
	v_exp_f32_e32 v159, v159
	v_exp_f32_e32 v160, v160
	v_exp_f32_e32 v161, v161
	v_exp_f32_e32 v162, v162
	v_exp_f32_e32 v163, v163
	v_sub_f32_e32 v156, 1.0, v156
	v_sub_f32_e32 v157, 1.0, v157
	v_sub_f32_e32 v158, 1.0, v158
	v_sub_f32_e32 v159, 1.0, v159
	v_sub_f32_e32 v160, 1.0, v160
	v_sub_f32_e32 v161, 1.0, v161
	v_sub_f32_e32 v162, 1.0, v162
	v_sub_f32_e32 v163, 1.0, v163
	v_exp_f32_e32 v204, v70
	v_exp_f32_e32 v205, v71
	v_exp_f32_e32 v206, v72
	v_exp_f32_e32 v207, v73
	v_exp_f32_e32 v208, v66
	v_exp_f32_e32 v209, v67
	v_exp_f32_e32 v210, v68
	v_exp_f32_e32 v211, v69
	v_sub_f32_dpp v126, v66, v70 row_newbcast:15 row_mask:0xf bank_mask:0xf
	v_sub_f32_dpp v127, v67, v71 row_newbcast:15 row_mask:0xf bank_mask:0xf
	v_sub_f32_dpp v128, v68, v72 row_newbcast:15 row_mask:0xf bank_mask:0xf
	v_sub_f32_dpp v129, v69, v73 row_newbcast:15 row_mask:0xf bank_mask:0xf
	v_sub_f32_dpp v130, v66, v66 row_newbcast:15 row_mask:0xf bank_mask:0xf
	v_sub_f32_dpp v131, v67, v67 row_newbcast:15 row_mask:0xf bank_mask:0xf
	v_sub_f32_dpp v132, v68, v68 row_newbcast:15 row_mask:0xf bank_mask:0xf
	v_sub_f32_dpp v133, v69, v69 row_newbcast:15 row_mask:0xf bank_mask:0xf
	v_mul_f32_e32 v196, v196, v204
	v_mul_f32_e32 v197, v197, v205
	v_mul_f32_e32 v198, v198, v206
	v_mul_f32_e32 v199, v199, v207
	v_mul_f32_e32 v200, v200, v208
	v_mul_f32_e32 v201, v201, v209
	v_mul_f32_e32 v202, v202, v210
	v_mul_f32_e32 v203, v203, v211
	v_min_f32_e64 v204, -v70, s23
	v_min_f32_e64 v205, -v71, s23
	v_min_f32_e64 v206, -v72, s23
	v_min_f32_e64 v207, -v73, s23
	v_min_f32_e64 v208, -v66, s23
	v_min_f32_e64 v209, -v67, s23
	v_min_f32_e64 v210, -v68, s23
	v_min_f32_e64 v211, -v69, s23
	v_exp_f32_e32 v126, v126
	v_exp_f32_e32 v127, v127
	v_exp_f32_e32 v128, v128
	v_exp_f32_e32 v129, v129
	v_exp_f32_e32 v130, v130
	v_exp_f32_e32 v131, v131
	v_exp_f32_e32 v132, v132
	v_exp_f32_e32 v133, v133
	v_exp_f32_e32 v204, v204
	v_exp_f32_e32 v205, v205
	v_exp_f32_e32 v206, v206
	v_exp_f32_e32 v207, v207
	v_exp_f32_e32 v208, v208
	v_exp_f32_e32 v209, v209
	v_exp_f32_e32 v210, v210
	v_exp_f32_e32 v211, v211
	v_exp_f32_e32 v212, v66
	v_exp_f32_e32 v213, v67
	v_exp_f32_e32 v214, v68
	v_exp_f32_e32 v215, v69
	v_mul_f32_e32 v126, v126, v156
	v_mul_f32_e32 v127, v127, v157
	v_mul_f32_e32 v128, v128, v158
	v_mul_f32_e32 v129, v129, v159
	v_mul_f32_e32 v130, v130, v160
	v_mul_f32_e32 v131, v131, v161
	v_mul_f32_e32 v132, v132, v162
	v_mul_f32_e32 v133, v133, v163
	v_mul_f32_e32 v204, v204, v156
	v_mul_f32_e32 v205, v205, v157
	v_mul_f32_e32 v206, v206, v158
	v_mul_f32_e32 v207, v207, v159
	v_mul_f32_e32 v208, v208, v160
	v_mul_f32_e32 v209, v209, v161
	v_mul_f32_e32 v210, v210, v162
	v_mul_f32_e32 v211, v211, v163
	v_lshl_add_u32 v216, v222, 1, s28
	v_cvt_pk_bf16_f32 v148, v196, v197
	v_cvt_pk_bf16_f32 v149, v198, v199
	v_cvt_pk_bf16_f32 v150, v200, v201
	v_cvt_pk_bf16_f32 v151, v202, v203
	v_cvt_pk_bf16_f32 v152, v204, v205
	v_cvt_pk_bf16_f32 v153, v206, v207
	v_cvt_pk_bf16_f32 v154, v208, v209
	v_cvt_pk_bf16_f32 v155, v210, v211
	v_cvt_pk_bf16_f32 v134, v126, v127
	v_cvt_pk_bf16_f32 v135, v128, v129
	v_cvt_pk_bf16_f32 v136, v130, v131
	v_cvt_pk_bf16_f32 v137, v132, v133
	ds_write_b64 v139, v[148:149]
	ds_write_b64 v139, v[150:151] offset:4352
	ds_write_b64 v139, v[152:153] offset:8704
	ds_write_b64 v139, v[154:155] offset:13056
	ds_write_b64 v138, v[134:135] offset:27648
	ds_write_b64 v138, v[136:137] offset:32768
	s_and_saveexec_b64 s[20:21], s[2:3]
	ds_write_b128 v216, v[212:215] offset:56832
	s_branch .LBB0_1329
